# P0 tail on workgroups 0-7 (SSM B/C table conversion): all 40 loads issued at once instead of a 24-step load->wait->store ladder; P3 stores widened to 16 B per lane with v_permlane16_swap
# speedup vs baseline: 1.0092x; 1.0092x over previous
; __device__ __forceinline__ void p0_prologue(const Args& a, LAS unsigned char* lds, int wave, int lane) {
;     ...
;     if (gt < NGRP * NST) {
;         const int g = gt >> 6, p = gt & 63;
;         const float dt = expf(a.in[9][g]), lr = a.in[7][gt], li = a.in[8][gt];
;         const float mag = expf(lr * dt); float sn, cs; sincos_small(li * dt, sn, cs);
;         const float ar = mag * cs, ai = mag * sn, den = lr * lr + li * li, nr = ar - 1.0f, ni = ai;
;         const float fr = (nr * lr + ni * li) / den, fi = (ni * lr - nr * li) / den;
;         ((f32x2*)(ws + WS_ATAB))[gt] = (f32x2){ar, ai};
;         float pr = ar, pi = ai;
; #pragma unroll
;         for (int i = 0; i < 8; ++i) { const float tr = pr * pr - pi * pi, ti = 2.0f * pr * pi; pr = tr; pi = ti; }
;         ((f32x2*)(ws + WS_ATAB2))[gt] = (f32x2){pr, pi};
;         bf16* BB = (bf16*)(ws + WS_BB); bf16* CM = (bf16*)(ws + WS_CM);
;         const int rre = g * 128 + (p >> 5) * 64 + (p & 31), rim = rre + 32;
;         const float* bre = a.in[10] + (size_t)gt * 16; const float* bim = a.in[11] + (size_t)gt * 16;
.LBB0_103:
	s_or_b64 exec, exec, s[0:1]
	s_movk_i32 s0, 0x1000
	v_cmp_gt_i32_e32 vcc, s0, v2
	v_and_b32_e32 v130, 31, v224
	s_and_saveexec_b64 s[4:5], vcc
	s_cbranch_execz .LBB0_105
	v_ashrrev_i32_e32 v0, 6, v2
	v_mov_b32_e32 v4, s62
	v_mov_b32_e32 v5, s63
	v_ashrrev_i32_e32 v1, 31, v0
	v_lshl_add_u64 v[4:5], v[0:1], 2, v[4:5]
	global_load_dword v9, v[4:5], off
	v_lshlrev_b64 v[4:5], 2, v[2:3]
	v_lshl_add_u64 v[6:7], s[90:91], 0, v[4:5]
	v_lshl_add_u64 v[4:5], s[60:61], 0, v[4:5]
	global_load_dword v22, v[6:7], off
	global_load_dword v23, v[4:5], off
	s_mov_b32 s10, 0x3fb8aa3b
	v_lshl_add_u64 v[6:7], v[2:3], 3, s[58:59]
	s_mov_b32 s11, 0x80000
	v_add_co_u32_e32 v10, vcc, s11, v6
	s_mov_b32 s12, 0x88000
	s_nop 0
	v_addc_co_u32_e32 v11, vcc, 0, v7, vcc
	v_add_co_u32_e32 v6, vcc, s12, v6
	s_mov_b32 s9, 0xc2ce8ed0
	s_nop 0
	v_addc_co_u32_e32 v7, vcc, 0, v7, vcc
	s_mov_b32 s8, 0x42b17218
	v_mov_b32_e32 v12, 0x7f800000
	s_mov_b32 s0, 0x37ccf5ce
	s_mov_b32 s1, 0x394ca1f9
	v_mov_b32_e32 v4, 0xbab6061a
	v_mov_b32_e32 v5, 0x3c08839e
	s_mov_b32 s6, 0x3d2aaaa5
	s_mov_b32 s7, 0xbe2aaaa3
	v_mov_b32_e32 v8, 2.0
	v_mov_b32_e32 v13, v8
	v_lshlrev_b64 v[2:3], 6, v[2:3]
	s_waitcnt vmcnt(2)
	v_mul_f32_e32 v14, 0x3fb8aa3b, v9
	v_fma_f32 v15, v9, s10, -v14
	v_rndne_f32_e32 v16, v14
	v_fmac_f32_e32 v15, 0x32a5705f, v9
	v_sub_f32_e32 v14, v14, v16
	v_add_f32_e32 v14, v14, v15
	v_cvt_i32_f32_e32 v16, v16
	v_exp_f32_e32 v14, v14
	v_cmp_ngt_f32_e32 vcc, s9, v9
	v_ldexp_f32 v14, v14, v16
	s_nop 0
	v_cndmask_b32_e32 v14, 0, v14, vcc
	v_cmp_nlt_f32_e32 vcc, s8, v9
	s_nop 1
	v_cndmask_b32_e32 v9, v12, v14, vcc
	s_waitcnt vmcnt(1)
	v_mul_f32_e32 v24, v9, v22
	s_waitcnt vmcnt(0)
	v_mul_f32_e32 v9, v9, v23
	v_mul_f32_e32 v14, 0x3fb8aa3b, v24
	v_mul_f32_e32 v15, 0x3f22f983, v9
	v_fma_f32 v16, v24, s10, -v14
	v_rndne_f32_e32 v17, v14
	v_rndne_f32_e32 v15, v15
	v_fmac_f32_e32 v16, 0x32a5705f, v24
	v_sub_f32_e32 v14, v14, v17
	v_fmamk_f32 v9, v15, 0xbfc90000, v9
	v_add_f32_e32 v14, v14, v16
	v_cvt_i32_f32_e32 v25, v17
	v_fmamk_f32 v9, v15, 0xb9fda000, v9
	v_exp_f32_e32 v27, v14
	v_cvt_i32_f32_e32 v26, v15
	v_fmamk_f32 v15, v15, 0xb3a22169, v9
	v_mul_f32_e32 v14, v15, v15
	v_pk_fma_f32 v[20:21], v[14:15], s[0:1], v[4:5]
	v_pk_fma_f32 v[4:5], v[14:15], s[0:1], v[4:5] op_sel_hi:[0,1,1] neg_lo:[1,0,0] neg_hi:[1,0,0]
	v_mov_b32_e32 v21, v5
	v_ldexp_f32 v25, v27, v25
	v_cmp_ngt_f32_e32 vcc, s9, v24
	v_mov_b32_e32 v17, v15
	v_fma_f32 v16, v14, -0.5, 1.0
	v_and_b32_e32 v9, 1, v26
	v_pk_mul_f32 v[18:19], v[14:15], v[14:15] op_sel_hi:[1,0]
	v_pk_fma_f32 v[4:5], v[14:15], v[20:21], s[6:7] op_sel_hi:[0,1,1]
	v_cndmask_b32_e32 v14, 0, v25, vcc
	v_cmp_nlt_f32_e32 vcc, s8, v24
	v_add_u32_e32 v28, 1, v26
	v_and_b32_e32 v26, 2, v26
	v_pk_fma_f32 v[4:5], v[18:19], v[4:5], v[16:17]
	v_cndmask_b32_e32 v12, v12, v14, vcc
	v_cmp_eq_u32_e32 vcc, 0, v9
	v_and_b32_e32 v28, 2, v28
	s_add_u32 s6, s58, 0x100000
	v_cndmask_b32_e32 v9, v5, v4, vcc
	v_cndmask_b32_e32 v4, v4, v5, vcc
	v_cmp_eq_u32_e32 vcc, 0, v26
	s_addc_u32 s7, s59, 0
	s_nop 0
	v_cndmask_b32_e64 v5, -v4, v4, vcc
	v_cmp_eq_u32_e32 vcc, 0, v28
	s_nop 1
	v_cndmask_b32_e64 v4, -v9, v9, vcc
	v_pk_mul_f32 v[4:5], v[12:13], v[4:5] op_sel_hi:[0,1]
	global_store_dwordx2 v[10:11], v[4:5], off
	v_mul_f32_e32 v10, v5, v5
	v_add_f32_e32 v9, v4, v4
	v_pk_fma_f32 v[10:11], v[4:5], v[4:5], v[10:11] op_sel_hi:[1,1,0] neg_lo:[0,0,1] neg_hi:[0,0,1]
	v_mul_f32_e32 v14, v5, v9
	v_mov_b32_e32 v9, v10
	v_mul_f32_e32 v15, v14, v14
	v_pk_mul_f32 v[16:17], v[10:11], v[8:9] op_sel_hi:[0,1]
	v_pk_fma_f32 v[10:11], v[10:11], v[8:9], v[14:15] op_sel_hi:[0,1,1] neg_lo:[0,0,1] neg_hi:[0,0,1]
	v_pk_mul_f32 v[14:15], v[16:17], v[14:15]
	v_mul_f32_e32 v10, v11, v11
	v_mov_b32_e32 v15, v11
	v_add_f32_e32 v9, v11, v11
	v_pk_fma_f32 v[10:11], v[14:15], v[14:15], v[10:11] op_sel_hi:[1,1,0] neg_lo:[1,0,0] neg_hi:[1,0,0]
	v_add_f32_e32 v4, -1.0, v4
	v_mul_f32_e32 v11, v14, v9
	v_mul_f32_e32 v12, v10, v10
	v_pk_fma_f32 v[14:15], v[10:11], v[10:11], v[12:13] op_sel_hi:[1,1,0] neg_lo:[1,0,0] neg_hi:[1,0,0]
	v_add_f32_e32 v16, v10, v10
	v_mov_b32_e32 v10, v11
	v_mov_b32_e32 v11, v15
	v_mov_b32_e32 v17, v15
	v_pk_mul_f32 v[10:11], v[10:11], v[16:17]
	s_nop 0
	v_pk_mov_b32 v[14:15], v[14:15], v[10:11] op_sel:[1,0]
	v_mov_b32_e32 v9, v10
	v_pk_mul_f32 v[16:17], v[14:15], v[8:9]
	v_pk_fma_f32 v[8:9], v[14:15], v[8:9], v[10:11] neg_lo:[1,0,0] neg_hi:[1,0,0]
	v_pk_mul_f32 v[10:11], v[10:11], v[16:17]
	v_mul_f32_e32 v8, v9, v9
	v_mov_b32_e32 v11, v9
	v_add_f32_e32 v12, v9, v9
	v_pk_fma_f32 v[8:9], v[10:11], v[10:11], v[8:9] op_sel_hi:[1,1,0] neg_lo:[1,0,0] neg_hi:[1,0,0]
	v_mul_f32_e32 v16, v22, v4
	v_mul_f32_e32 v9, v10, v12
	v_add_f32_e32 v11, v8, v8
	v_mul_f32_e32 v10, v9, v9
	v_pk_fma_f32 v[14:15], v[8:9], v[8:9], v[10:11] op_sel_hi:[1,1,0] neg_lo:[0,0,1] neg_hi:[0,0,1]
	v_mul_f32_e32 v4, v23, v4
	v_mov_b32_e32 v8, v14
	v_mov_b32_e32 v10, v14
	v_pk_mul_f32 v[8:9], v[8:9], v[10:11]
	v_fmac_f32_e32 v16, v23, v5
	v_pk_mov_b32 v[10:11], v[8:9], v[14:15] op_sel:[1,0]
	v_mov_b32_e32 v12, v9
	v_pk_add_f32 v[14:15], v[10:11], v[10:11]
	v_pk_fma_f32 v[10:11], v[10:11], v[12:13], v[8:9] neg_lo:[1,0,0] neg_hi:[1,0,0]
	v_pk_mul_f32 v[8:9], v[8:9], v[14:15]
	v_lshlrev_b32_e32 v12, 1, v224
	v_mov_b32_e32 v11, v9
	global_store_dwordx2 v[6:7], v[10:11], off
	v_lshl_add_u64 v[6:7], s[66:67], 0, v[2:3]
	v_lshl_add_u64 v[2:3], s[64:65], 0, v[2:3]
	global_load_dwordx4 v[32:35], v[6:7], off
	global_load_dwordx4 v[36:39], v[6:7], off offset:16
	global_load_dwordx4 v[40:43], v[6:7], off offset:32
	global_load_dwordx4 v[44:47], v[6:7], off offset:48
	global_load_dwordx4 v[48:51], v[2:3], off
; __device__ __forceinline__ unsigned cvt_pk(float lo, float hi) { unsigned r; asm volatile("v_cvt_pk_bf16_f32 %0, %1, %2" : "=v"(r) : "v"(lo), "v"(hi)); return r; }
; __device__ __forceinline__ void p0_prologue(const Args& a, LAS unsigned char* lds, int wave, int lane) {
;     ...
;         const float fr = (nr * lr + ni * li) / den, fi = (ni * lr - nr * li) / den;
;         ((f32x2*)(ws + WS_ATAB))[gt] = (f32x2){ar, ai};
;         float pr = ar, pi = ai;
; #pragma unroll
;         for (int i = 0; i < 8; ++i) { const float tr = pr * pr - pi * pi, ti = 2.0f * pr * pi; pr = tr; pi = ti; }
;         ((f32x2*)(ws + WS_ATAB2))[gt] = (f32x2){pr, pi};
;         bf16* BB = (bf16*)(ws + WS_BB); bf16* CM = (bf16*)(ws + WS_CM);
;         const int rre = g * 128 + (p >> 5) * 64 + (p & 31), rim = rre + 32;
;         const float* bre = a.in[10] + (size_t)gt * 16; const float* bim = a.in[11] + (size_t)gt * 16;
; #pragma unroll
;         for (int c = 0; c < 16; c += 2) {
;             const float br0 = bre[c], bi0 = bim[c], br1 = bre[c + 1], bi1 = bim[c + 1];
;             *(unsigned*)(BB + (size_t)rre * 16 + c) = cvt_pk(fr * br0 - fi * bi0, fr * br1 - fi * bi1);
;             *(unsigned*)(BB + (size_t)rim * 16 + c) = cvt_pk(fr * bi0 + fi * br0, fr * bi1 + fi * br1);
;         }
; #pragma unroll
;         for (int c = 0; c < 16; ++c) {
;             const float cr = a.in[12][((size_t)g * 16 + c) * 64 + p], ci = a.in[13][((size_t)g * 16 + c) * 64 + p];
;             *(unsigned*)(CM + ((size_t)g * 16 + c) * 128 + 2 * p) = cvt_pk(cr, -ci);
;         }
	global_load_dwordx4 v[52:55], v[2:3], off offset:16
	global_load_dwordx4 v[56:59], v[2:3], off offset:32
	global_load_dwordx4 v[60:63], v[2:3], off offset:48
	v_lshlrev_b32_e32 v13, 7, v0
	v_and_b32_e32 v12, 64, v12
	v_or3_b32 v12, v13, v12, v130
	v_ashrrev_i32_e32 v13, 31, v12
	v_lshlrev_b64 v[14:15], 5, v[12:13]
	v_lshlrev_b64 v[0:1], 12, v[0:1]
	v_lshlrev_b32_e32 v100, 2, v128
	v_or_b32_e32 v100, v0, v100
	v_mov_b32_e32 v101, v1
	v_lshl_add_u64 v[96:97], s[68:69], 0, v[100:101]
	v_lshl_add_u64 v[98:99], s[70:71], 0, v[100:101]
	global_load_dword v64, v[96:97], off
	global_load_dword v65, v[96:97], off offset:256
	global_load_dword v66, v[96:97], off offset:512
	global_load_dword v67, v[96:97], off offset:768
	global_load_dword v68, v[96:97], off offset:1024
	global_load_dword v69, v[96:97], off offset:1280
	global_load_dword v70, v[96:97], off offset:1536
	global_load_dword v71, v[96:97], off offset:1792
	global_load_dword v72, v[96:97], off offset:2048
	global_load_dword v73, v[96:97], off offset:2304
	global_load_dword v74, v[96:97], off offset:2560
	global_load_dword v75, v[96:97], off offset:2816
	global_load_dword v76, v[96:97], off offset:3072
	global_load_dword v77, v[96:97], off offset:3328
	global_load_dword v78, v[96:97], off offset:3584
	global_load_dword v79, v[96:97], off offset:3840
	global_load_dword v80, v[98:99], off
	global_load_dword v81, v[98:99], off offset:256
	global_load_dword v82, v[98:99], off offset:512
	global_load_dword v83, v[98:99], off offset:768
	global_load_dword v84, v[98:99], off offset:1024
	global_load_dword v85, v[98:99], off offset:1280
	global_load_dword v86, v[98:99], off offset:1536
	global_load_dword v87, v[98:99], off offset:1792
	global_load_dword v88, v[98:99], off offset:2048
	global_load_dword v89, v[98:99], off offset:2304
	global_load_dword v90, v[98:99], off offset:2560
	global_load_dword v91, v[98:99], off offset:2816
	global_load_dword v92, v[98:99], off offset:3072
	global_load_dword v93, v[98:99], off offset:3328
	global_load_dword v94, v[98:99], off offset:3584
	global_load_dword v95, v[98:99], off offset:3840
	v_mul_f32_e32 v13, v23, v23
	v_fmac_f32_e32 v13, v22, v22
	v_fma_f32 v4, v22, v5, -v4
	v_div_scale_f32 v5, s[0:1], v13, v13, v16
	v_div_scale_f32 v18, s[0:1], v13, v13, v4
	v_rcp_f32_e32 v19, v5
	v_rcp_f32_e32 v20, v18
	v_div_scale_f32 v17, vcc, v16, v13, v16
	v_fma_f32 v22, -v5, v19, 1.0
	v_fma_f32 v23, -v18, v20, 1.0
	v_fmac_f32_e32 v19, v22, v19
	v_div_scale_f32 v21, s[0:1], v4, v13, v4
	v_fmac_f32_e32 v20, v23, v20
	v_mul_f32_e32 v22, v17, v19
	v_mul_f32_e32 v23, v21, v20
	v_fma_f32 v24, -v5, v22, v17
	v_fma_f32 v25, -v18, v23, v21
	v_fmac_f32_e32 v22, v24, v19
	v_fmac_f32_e32 v23, v25, v20
	v_fma_f32 v5, -v5, v22, v17
	v_fma_f32 v17, -v18, v23, v21
	v_div_fmas_f32 v5, v5, v19, v22
	s_mov_b64 vcc, s[0:1]
	v_div_fixup_f32 v16, v5, v13, v16
	v_div_fmas_f32 v5, v17, v20, v23
	v_div_fixup_f32 v17, v5, v13, v4
	v_lshl_add_u64 v[14:15], s[6:7], 0, v[14:15]
	s_add_u32 s8, s58, 0x140000
	s_addc_u32 s9, s59, 0
	v_lshl_add_u64 v[100:101], s[8:9], 0, v[100:101]
	s_waitcnt vmcnt(32)
; __device__ __forceinline__ unsigned cvt_pk(float lo, float hi) { unsigned r; asm volatile("v_cvt_pk_bf16_f32 %0, %1, %2" : "=v"(r) : "v"(lo), "v"(hi)); return r; }
; __device__ __forceinline__ void p0_prologue(const Args& a, LAS unsigned char* lds, int wave, int lane) {
;     ...
;         for (int c = 0; c < 16; c += 2) {
;             const float br0 = bre[c], bi0 = bim[c], br1 = bre[c + 1], bi1 = bim[c + 1];
;             *(unsigned*)(BB + (size_t)rre * 16 + c) = cvt_pk(fr * br0 - fi * bi0, fr * br1 - fi * bi1);
;             *(unsigned*)(BB + (size_t)rim * 16 + c) = cvt_pk(fr * bi0 + fi * br0, fr * bi1 + fi * br1);
;         }
; #pragma unroll
;         for (int c = 0; c < 16; ++c) {
;             const float cr = a.in[12][((size_t)g * 16 + c) * 64 + p], ci = a.in[13][((size_t)g * 16 + c) * 64 + p];
;             *(unsigned*)(CM + ((size_t)g * 16 + c) * 128 + 2 * p) = cvt_pk(cr, -ci);
;         }
	v_mul_f32_e32 v4, v32, v17
	v_mul_f32_e32 v5, v33, v17
	v_mul_f32_e32 v8, v32, v16
	v_mul_f32_e32 v9, v33, v16
	v_fma_f32 v4, v48, v16, -v4
	v_fma_f32 v5, v49, v16, -v5
	v_fmac_f32_e32 v8, v48, v17
	v_fmac_f32_e32 v9, v49, v17
	v_cvt_pk_bf16_f32 v104, v4, v5
	v_cvt_pk_bf16_f32 v116, v8, v9
	v_mul_f32_e32 v4, v34, v17
	v_mul_f32_e32 v5, v35, v17
	v_mul_f32_e32 v8, v34, v16
	v_mul_f32_e32 v9, v35, v16
	v_fma_f32 v4, v50, v16, -v4
	v_fma_f32 v5, v51, v16, -v5
	v_fmac_f32_e32 v8, v50, v17
	v_fmac_f32_e32 v9, v51, v17
	v_cvt_pk_bf16_f32 v105, v4, v5
	v_cvt_pk_bf16_f32 v117, v8, v9
	v_mul_f32_e32 v4, v36, v17
	v_mul_f32_e32 v5, v37, v17
	v_mul_f32_e32 v8, v36, v16
	v_mul_f32_e32 v9, v37, v16
	v_fma_f32 v4, v52, v16, -v4
	v_fma_f32 v5, v53, v16, -v5
	v_fmac_f32_e32 v8, v52, v17
	v_fmac_f32_e32 v9, v53, v17
	v_cvt_pk_bf16_f32 v106, v4, v5
	v_cvt_pk_bf16_f32 v118, v8, v9
	v_mul_f32_e32 v4, v38, v17
	v_mul_f32_e32 v5, v39, v17
	v_mul_f32_e32 v8, v38, v16
	v_mul_f32_e32 v9, v39, v16
	v_fma_f32 v4, v54, v16, -v4
	v_fma_f32 v5, v55, v16, -v5
	v_fmac_f32_e32 v8, v54, v17
	v_fmac_f32_e32 v9, v55, v17
	v_cvt_pk_bf16_f32 v107, v4, v5
	v_cvt_pk_bf16_f32 v119, v8, v9
	v_mul_f32_e32 v4, v40, v17
	v_mul_f32_e32 v5, v41, v17
	v_mul_f32_e32 v8, v40, v16
	v_mul_f32_e32 v9, v41, v16
	v_fma_f32 v4, v56, v16, -v4
	v_fma_f32 v5, v57, v16, -v5
	v_fmac_f32_e32 v8, v56, v17
	v_fmac_f32_e32 v9, v57, v17
	v_cvt_pk_bf16_f32 v108, v4, v5
	v_cvt_pk_bf16_f32 v120, v8, v9
	v_mul_f32_e32 v4, v42, v17
	v_mul_f32_e32 v5, v43, v17
	v_mul_f32_e32 v8, v42, v16
	v_mul_f32_e32 v9, v43, v16
	v_fma_f32 v4, v58, v16, -v4
	v_fma_f32 v5, v59, v16, -v5
	v_fmac_f32_e32 v8, v58, v17
	v_fmac_f32_e32 v9, v59, v17
	v_cvt_pk_bf16_f32 v109, v4, v5
	v_cvt_pk_bf16_f32 v121, v8, v9
	v_mul_f32_e32 v4, v44, v17
	v_mul_f32_e32 v5, v45, v17
	v_mul_f32_e32 v8, v44, v16
	v_mul_f32_e32 v9, v45, v16
	v_fma_f32 v4, v60, v16, -v4
	v_fma_f32 v5, v61, v16, -v5
	v_fmac_f32_e32 v8, v60, v17
	v_fmac_f32_e32 v9, v61, v17
	v_cvt_pk_bf16_f32 v110, v4, v5
	v_cvt_pk_bf16_f32 v122, v8, v9
	v_mul_f32_e32 v4, v46, v17
	v_mul_f32_e32 v5, v47, v17
	v_mul_f32_e32 v8, v46, v16
	v_mul_f32_e32 v9, v47, v16
	v_fma_f32 v4, v62, v16, -v4
	v_fma_f32 v5, v63, v16, -v5
	v_fmac_f32_e32 v8, v62, v17
	v_fmac_f32_e32 v9, v63, v17
	v_cvt_pk_bf16_f32 v111, v4, v5
	v_cvt_pk_bf16_f32 v123, v8, v9
	global_store_dwordx4 v[14:15], v[104:107], off
	global_store_dwordx4 v[14:15], v[108:111], off offset:16
	global_store_dwordx4 v[14:15], v[116:119], off offset:1024
	global_store_dwordx4 v[14:15], v[120:123], off offset:1040
	s_waitcnt vmcnt(4)
	v_xor_b32_e32 v80, 0x80000000, v80
	v_xor_b32_e32 v81, 0x80000000, v81
	v_xor_b32_e32 v82, 0x80000000, v82
	v_xor_b32_e32 v83, 0x80000000, v83
	v_xor_b32_e32 v84, 0x80000000, v84
	v_xor_b32_e32 v85, 0x80000000, v85
	v_xor_b32_e32 v86, 0x80000000, v86
	v_xor_b32_e32 v87, 0x80000000, v87
	v_xor_b32_e32 v88, 0x80000000, v88
	v_xor_b32_e32 v89, 0x80000000, v89
	v_xor_b32_e32 v90, 0x80000000, v90
	v_xor_b32_e32 v91, 0x80000000, v91
	v_xor_b32_e32 v92, 0x80000000, v92
	v_xor_b32_e32 v93, 0x80000000, v93
	v_xor_b32_e32 v94, 0x80000000, v94
	v_xor_b32_e32 v95, 0x80000000, v95
	v_cvt_pk_bf16_f32 v64, v64, v80
	v_cvt_pk_bf16_f32 v65, v65, v81
	v_cvt_pk_bf16_f32 v66, v66, v82
	v_cvt_pk_bf16_f32 v67, v67, v83
	v_cvt_pk_bf16_f32 v68, v68, v84
	v_cvt_pk_bf16_f32 v69, v69, v85
	v_cvt_pk_bf16_f32 v70, v70, v86
	v_cvt_pk_bf16_f32 v71, v71, v87
	v_cvt_pk_bf16_f32 v72, v72, v88
	v_cvt_pk_bf16_f32 v73, v73, v89
	v_cvt_pk_bf16_f32 v74, v74, v90
	v_cvt_pk_bf16_f32 v75, v75, v91
	v_cvt_pk_bf16_f32 v76, v76, v92
	v_cvt_pk_bf16_f32 v77, v77, v93
	v_cvt_pk_bf16_f32 v78, v78, v94
	v_cvt_pk_bf16_f32 v79, v79, v95
	global_store_dword v[100:101], v64, off
	global_store_dword v[100:101], v65, off offset:256
	global_store_dword v[100:101], v66, off offset:512
	global_store_dword v[100:101], v67, off offset:768
	global_store_dword v[100:101], v68, off offset:1024
	global_store_dword v[100:101], v69, off offset:1280
	global_store_dword v[100:101], v70, off offset:1536
	global_store_dword v[100:101], v71, off offset:1792
	global_store_dword v[100:101], v72, off offset:2048
	global_store_dword v[100:101], v73, off offset:2304
	global_store_dword v[100:101], v74, off offset:2560
	global_store_dword v[100:101], v75, off offset:2816
	global_store_dword v[100:101], v76, off offset:3072
	global_store_dword v[100:101], v77, off offset:3328
	global_store_dword v[100:101], v78, off offset:3584
	global_store_dword v[100:101], v79, off offset:3840
	v_mov_b32_e32 v3, 0

; #define LAS __attribute__((address_space(3)))
; template <bool FINAL>
; __device__ __forceinline__ void ssm_item(const Args& a, LAS unsigned char* lds, int item, int wave, int lane) {
;     ...
;     if (FINAL) {
; #pragma unroll
;         for (int k = 0; k < 4; ++k) cmf[k] = *(const bf16x8*)((const bf16*)(ws + WS_CM) + ((size_t)g * 16 + (lane & 15)) * 128 + 32 * k + 8 * (lane >> 4));
;         dsk = *(const f32x4*)(a.in[14] + g * 16 + 4 * (lane >> 4));
;         const f32x2 t0 = ((const f32x2*)(ws + WS_ATAB2))[g * 64 + j], t1 = ((const f32x2*)(ws + WS_ATAB2))[g * 64 + 32 + j];
;         const f32x2 m0 = ((const f32x2*)(ws + WS_SMETA))[g * 64 + j], m1 = ((const f32x2*)(ws + WS_SMETA))[g * 64 + 32 + j];
;         float c0r = m0.x, c0i = m0.y, c1r = m1.x, c1i = m1.y;
;         const f32x2* Eb = (const f32x2*)E + ((size_t)((b0 + hi) * 64 + g) * NCHUNK) * 64;
; #pragma unroll
;         for (int half = 0; half < 2; ++half) {
;             if (half * 16 < c0) {
;                 f32x2 e0[16], e1[16];
; #pragma unroll
;                 for (int c = 0; c < 16; ++c) { const int cc = half * 16 + c < NCHUNK - 1 ? half * 16 + c : NCHUNK - 2; e0[c] = Eb[cc * 64 + j]; e1[c] = Eb[cc * 64 + 32 + j]; }
; #pragma unroll
;                 for (int c = 0; c < 16; ++c) if (half * 16 + c < c0) {
;                     const float n0r = fmaf(t0.x, c0r, fmaf(-t0.y, c0i, e0[c].x)), n0i = fmaf(t0.x, c0i, fmaf(t0.y, c0r, e0[c].y));
;                     const float n1r = fmaf(t1.x, c1r, fmaf(-t1.y, c1i, e1[c].x)), n1i = fmaf(t1.x, c1i, fmaf(t1.y, c1r, e1[c].y));
;                     c0r = n0r; c0i = n0i; c1r = n1r; c1i = n1i; }
;             }
;         }
;         const f32x2 ec0 = Eb[c0 * 64 + j], ec1 = Eb[c0 * 64 + 32 + j];
;         s0r = (f32x2){c0r, fmaf(t0.x, c0r, fmaf(-t0.y, c0i, ec0.x))}; s0i = (f32x2){c0i, fmaf(t0.x, c0i, fmaf(t0.y, c0r, ec0.y))};
;         s1r = (f32x2){c1r, fmaf(t1.x, c1r, fmaf(-t1.y, c1i, ec1.x))}; s1i = (f32x2){c1i, fmaf(t1.x, c1i, fmaf(t1.y, c1r, ec1.y))};
;     }
;     const int bsel = (j >> 2) & 1, csel = j & 1, tt = ((j & 3) >> 1) + 2 * (j >> 3);
;     const size_t urow0 = meta ? (size_t)META_ROW + tt : (size_t)(b0 + bsel) * SEQ + (size_t)(c0 + csel) * CHUNK + tt;
;     const bf16* up = U + urow0 * DM + g * 16 + 8 * hi;
;     LAS unsigned char* sl = lds + wave * (32 * SP);
;     const int nsteps = meta ? 2 : CHUNK / 8;
.LBB0_338:
	s_lshl_b32 s21, s20, 7
	s_lshl_b32 s22, s20, 6
	s_and_b32 s21, s21, 0x4000
	s_and_b32 s24, s22, 0x1e00
	s_lshl_b32 s22, s40, 4
	v_or_b32_e32 v6, s21, v161
	s_and_b32 s22, s22, 0x380
	v_or_b32_e32 v6, s24, v6
	s_add_i32 s22, s14, s22
	v_lshlrev_b32_e32 v106, 11, v6
	s_lshl_b32 s22, s22, 1
	s_mov_b32 s23, s11
	s_or_b32 s21, s24, s21
	v_lshl_add_u64 v[6:7], v[106:107], 0, s[22:23]
	v_add_lshl_u32 v106, s21, v241, 11
	s_lshl_b32 s21, s13, 6
	v_or_b32_e32 v14, s21, v130
	v_lshl_add_u64 v[8:9], v[106:107], 0, s[22:23]
	v_lshlrev_b32_e32 v106, 3, v14
	v_or_b32_e32 v16, s21, v104
	v_lshl_add_u64 v[14:15], v[4:5], 0, v[106:107]
	v_lshlrev_b32_e32 v106, 3, v16
	v_lshl_add_u64 v[4:5], v[4:5], 0, v[106:107]
	global_load_dwordx2 v[206:207], v[14:15], off
	global_load_dwordx2 v[204:205], v[4:5], off
	v_or_b32_e32 v4, s12, v163
	v_or_b32_e32 v5, s13, v165
	v_lshlrev_b32_e32 v4, 13, v4
	v_lshlrev_b32_e32 v5, 8, v5
	v_or_b32_e32 v14, s13, v169
	v_or3_b32 v4, v4, v5, v167
	s_lshl_b32 s12, s12, 13
	v_lshlrev_b32_e32 v14, 8, v14
	v_lshlrev_b32_e32 v106, 11, v4
	v_or3_b32 v16, v14, s12, v131
	v_lshl_add_u64 v[4:5], s[52:53], 0, v[106:107]
	v_lshlrev_b32_e32 v106, 11, v16
	s_lshl_b32 s10, s10, 1
	v_lshl_add_u64 v[14:15], s[52:53], 0, v[106:107]
	v_lshl_add_u64 v[4:5], v[4:5], 0, s[10:11]
	v_mov_b32_e32 v189, v107
	v_lshl_add_u64 v[14:15], v[14:15], 0, s[10:11]
	v_mov_b32_e32 v191, v107
	v_lshl_add_u64 v[4:5], v[4:5], 0, v[188:189]
	v_lshl_add_u64 v[14:15], v[14:15], 0, v[190:191]
	global_load_dwordx4 v[100:103], v[4:5], off
	global_load_dwordx2 v[218:219], v[14:15], off
	v_add_co_u32_e32 v4, vcc, 0x1000000, v14
	v_xor_b32_e32 v202, 0x80000000, v195
	s_nop 0
	v_addc_co_u32_e32 v5, vcc, 0, v15, vcc
	global_load_dwordx2 v[212:213], v[4:5], off
	v_xor_b32_e32 v196, 0x80000000, v193
	v_mov_b32_e32 v200, v195
	v_mov_b32_e32 v201, v195
	v_mov_b32_e32 v198, v193
	v_mov_b32_e32 v199, v193
	v_mov_b32_e32 v195, v194
	v_mov_b32_e32 v193, v192
	s_waitcnt vmcnt(6)
	v_mov_b32_e32 v216, v10
	s_waitcnt vmcnt(5)
	v_mov_b32_e32 v214, v12
	v_mov_b32_e32 v203, v202
	v_mov_b32_e32 v197, v196
	v_lshl_add_u64 v[208:209], v[114:115], 0, v[6:7]
	v_lshl_add_u64 v[210:211], v[116:117], 0, v[8:9]
	v_lshlrev_b32_e32 v106, 10, v16
	s_mov_b64 s[12:13], 0
	s_waitcnt vmcnt(4)
	v_fma_f32 v217, -v3, v11, v206
	v_fmac_f32_e32 v207, v3, v10
	s_waitcnt vmcnt(3)
	v_fma_f32 v215, -v1, v13, v204
	v_fmac_f32_e32 v205, v1, v12
	v_fmac_f32_e32 v217, v2, v10
	v_fmac_f32_e32 v207, v2, v11
	v_fmac_f32_e32 v215, v0, v12
	v_fmac_f32_e32 v205, v0, v13
	v_mov_b32_e32 v206, v11
	v_mov_b32_e32 v204, v13
	v_subrev_u32_e32 v137, s58, v208
	v_bfe_u32 v145, v224, 4, 2
	v_lshlrev_b32_e32 v147, 3, v145
	v_sub_u32_e32 v137, v137, v147
	v_lshrrev_b32_e32 v147, 1, v145
	v_lshl_add_u32 v137, v147, 4, v137
	v_and_b32_e32 v147, 1, v145
	v_lshl_add_u32 v137, v147, 24, v137
	v_subrev_u32_e32 v139, s58, v210
	s_add_u32 s76, s58, 0xd104000
	s_addc_u32 s77, s59, 0
	s_add_u32 s78, s58, 0xe104000
	s_addc_u32 s79, s59, 0
	s_add_u32 s66, s58, 0xd108000
	s_addc_u32 s67, s59, 0
	s_add_u32 s68, s58, 0xe108000
	s_addc_u32 s69, s59, 0
	s_add_u32 s70, s58, 0x6e00000
	s_addc_u32 s71, s59, 0
	s_add_u32 s74, s58, 0x7e00000
	s_addc_u32 s75, s59, 0
	global_load_dwordx4 v[248:251], v139, s[58:59]
	s_lshl_b32 s80, s33, 10
	s_add_i32 s80, s80, 0x11000
	v_and_b32_e32 v147, 63, v224
	v_and_b32_e32 v141, 31, v147
	v_lshlrev_b32_e32 v141, 5, v141
	v_lshrrev_b32_e32 v145, 5, v147
	v_lshl_or_b32 v141, v145, 4, v141
	v_add_u32_e32 v141, s80, v141
	v_and_b32_e32 v143, 6, v147
	v_lshlrev_b32_e32 v143, 2, v143
	v_and_b32_e32 v145, 1, v147
	v_lshl_or_b32 v143, v145, 1, v143
	v_bfe_u32 v145, v147, 3, 1
	v_or_b32_e32 v143, v143, v145
	v_lshlrev_b32_e32 v143, 5, v143
	v_lshrrev_b32_e32 v145, 5, v147
	v_lshl_or_b32 v143, v145, 4, v143
	v_bfe_u32 v145, v147, 4, 1
	v_lshl_or_b32 v143, v145, 3, v143
	v_add_u32_e32 v143, s80, v143
	s_mov_b32 s62, 0xbdd2d3e8
	s_mov_b32 s63, 0xbdd2d3e8
	s_mov_b32 s64, 0x3f800000
	s_mov_b32 s65, 0x3f800000
	v_mov_b32_e32 v246, 0xc0135761
	v_add_u32_e32 v245, 0x440, v242
	v_add_u32_e32 v247, 0x880, v242
	v_add_u32_e32 v106, 0xcc0, v242
	v_add_u32_e32 v139, 0x4000, v139
	s_mov_b32 s12, 0
	s_waitcnt vmcnt(0)
.Lp3_step:
	s_waitcnt vmcnt(3)
	ds_write_b128 v141, v[100:103]
	ds_read_b64 v[252:253], v143
	ds_read_b64 v[254:255], v143 offset:128
	v_mfma_f32_32x32x16_bf16 v[0:15], v[100:103], v[88:91], 0
	v_mfma_f32_32x32x16_bf16 v[16:31], v[100:103], v[92:95], 0
	v_mfma_f32_32x32x16_bf16 v[32:47], v[100:103], v[96:99], 0
	v_mfma_f32_32x32x16_bf16 v[48:63], v[100:103], v[84:87], 0
	s_nop 15
	global_load_dwordx4 v[100:103], v139, s[58:59]
	v_add_u32_e32 v139, 0x4000, v139
	v_pk_fma_f32 v[0:1], v[202:203], v[206:207], v[0:1]
	v_pk_fma_f32 v[16:17], v[200:201], v[216:217], v[16:17]
	v_pk_fma_f32 v[32:33], v[196:197], v[204:205], v[32:33]
	v_pk_fma_f32 v[48:49], v[198:199], v[214:215], v[48:49]
	v_pk_fma_f32 v[0:1], v[194:195], v[216:217], v[0:1]
	v_pk_fma_f32 v[16:17], v[194:195], v[206:207], v[16:17]
	v_pk_fma_f32 v[32:33], v[192:193], v[214:215], v[32:33]
	v_pk_fma_f32 v[48:49], v[192:193], v[204:205], v[48:49]
	v_pk_fma_f32 v[2:3], v[202:203], v[16:17], v[2:3]
	v_pk_fma_f32 v[18:19], v[200:201], v[0:1], v[18:19]
	v_pk_fma_f32 v[34:35], v[196:197], v[48:49], v[34:35]
	v_pk_fma_f32 v[50:51], v[198:199], v[32:33], v[50:51]
	v_pk_fma_f32 v[2:3], v[194:195], v[0:1], v[2:3]
	v_pk_fma_f32 v[18:19], v[194:195], v[16:17], v[18:19]
	v_pk_fma_f32 v[34:35], v[192:193], v[32:33], v[34:35]
	v_pk_fma_f32 v[50:51], v[192:193], v[48:49], v[50:51]
	v_cvt_pk_bf16_f32 v119, v0, v16
	v_cvt_pk_bf16_f32 v121, v32, v48
	v_cvt_pk_bf16_f32 v123, v1, v17
; #define LAS __attribute__((address_space(3)))
; __device__ __forceinline__ unsigned cvt_pk(float lo, float hi) { unsigned r; asm volatile("v_cvt_pk_bf16_f32 %0, %1, %2" : "=v"(r) : "v"(lo), "v"(hi)); return r; }
; #define LDS_WAIT() asm volatile("s_waitcnt lgkmcnt(0)" ::: "memory")
; __device__ __forceinline__ f32x2 pk_fma(f32x2 a, f32x2 b, f32x2 c) { return __builtin_elementwise_fma(a, b, c); }
; template <bool FINAL>
; __device__ __forceinline__ void ssm_item(const Args& a, LAS unsigned char* lds, int item, int wave, int lane) {
;     ...
;         for (int t = 0; t < 8; ++t) {
;             const f32x2 x0r = (f32x2){X[0][2 * t], X[0][2 * t + 1]}, x0i = (f32x2){X[1][2 * t], X[1][2 * t + 1]}, x1r = (f32x2){X[2][2 * t], X[2][2 * t + 1]}, x1i = (f32x2){X[3][2 * t], X[3][2 * t + 1]};
;             const f32x2 n0r = pk_fma(a0x, s0r, pk_fma(na0y, s0i, x0r)), n0i = pk_fma(a0x, s0i, pk_fma(a0y, s0r, x0i));
;             const f32x2 n1r = pk_fma(a1x, s1r, pk_fma(na1y, s1i, x1r)), n1i = pk_fma(a1x, s1i, pk_fma(a1y, s1r, x1i));
;             s0r = n0r; s0i = n0i; s1r = n1r; s1i = n1i;
;             if (FINAL) {
;                 LAS unsigned char* r0 = sl + ((hi * 2 + 0) * 8 + t) * SP; LAS unsigned char* r1 = sl + ((hi * 2 + 1) * 8 + t) * SP;
;                 *(LAS unsigned*)(r0 + j * 4) = cvt_pk(n0r.x, n0i.x); *(LAS unsigned*)(r0 + (32 + j) * 4) = cvt_pk(n1r.x, n1i.x);
;                 *(LAS unsigned*)(r1 + j * 4) = cvt_pk(n0r.y, n0i.y); *(LAS unsigned*)(r1 + (32 + j) * 4) = cvt_pk(n1r.y, n1i.y); }
;         }
;         if (FINAL) {
;             LDS_WAIT(); asm volatile("" ::: "memory");
; #pragma unroll
;             for (int bh = 0; bh < 2; ++bh) {
;                 f32x4 Y = (f32x4){0.f, 0.f, 0.f, 0.f};
; #pragma unroll
;                 for (int k = 0; k < 4; ++k) { const bf16x8 sf = *(const LAS bf16x8*)(sl + (bh * 16 + (lane & 15)) * SP + (32 * k + 8 * (lane >> 4)) * 2);
;                     Y = __builtin_amdgcn_mfma_f32_16x16x32_bf16(cmf[k], sf, Y, 0, 0, 0); }
	v_cvt_pk_bf16_f32 v125, v33, v49
	ds_write2_b32 v242, v119, v121 offset0:0 offset1:32
	ds_write2_b32 v247, v123, v125 offset0:0 offset1:32
	v_pk_fma_f32 v[4:5], v[202:203], v[18:19], v[4:5]
	v_pk_fma_f32 v[20:21], v[200:201], v[2:3], v[20:21]
	v_pk_fma_f32 v[36:37], v[196:197], v[50:51], v[36:37]
	v_pk_fma_f32 v[52:53], v[198:199], v[34:35], v[52:53]
	v_pk_fma_f32 v[4:5], v[194:195], v[2:3], v[4:5]
	v_pk_fma_f32 v[20:21], v[194:195], v[18:19], v[20:21]
	v_pk_fma_f32 v[36:37], v[192:193], v[34:35], v[36:37]
	v_pk_fma_f32 v[52:53], v[192:193], v[50:51], v[52:53]
	v_cvt_pk_bf16_f32 v127, v2, v18
	v_cvt_pk_bf16_f32 v129, v34, v50
	v_cvt_pk_bf16_f32 v133, v3, v19
	v_cvt_pk_bf16_f32 v135, v35, v51
	ds_write2_b32 v242, v127, v129 offset0:68 offset1:100
	ds_write2_b32 v247, v133, v135 offset0:68 offset1:100
	v_pk_fma_f32 v[6:7], v[202:203], v[20:21], v[6:7]
	v_pk_fma_f32 v[22:23], v[200:201], v[4:5], v[22:23]
	v_pk_fma_f32 v[38:39], v[196:197], v[52:53], v[38:39]
	v_pk_fma_f32 v[54:55], v[198:199], v[36:37], v[54:55]
	v_pk_fma_f32 v[6:7], v[194:195], v[4:5], v[6:7]
	v_pk_fma_f32 v[22:23], v[194:195], v[20:21], v[22:23]
	v_pk_fma_f32 v[38:39], v[192:193], v[36:37], v[38:39]
	v_pk_fma_f32 v[54:55], v[192:193], v[52:53], v[54:55]
	v_cvt_pk_bf16_f32 v119, v4, v20
	v_cvt_pk_bf16_f32 v121, v36, v52
	v_cvt_pk_bf16_f32 v123, v5, v21
	v_cvt_pk_bf16_f32 v125, v37, v53
	ds_write2_b32 v242, v119, v121 offset0:136 offset1:168
	ds_write2_b32 v247, v123, v125 offset0:136 offset1:168
	v_pk_fma_f32 v[8:9], v[202:203], v[22:23], v[8:9]
	v_pk_fma_f32 v[24:25], v[200:201], v[6:7], v[24:25]
	v_pk_fma_f32 v[40:41], v[196:197], v[54:55], v[40:41]
	v_pk_fma_f32 v[56:57], v[198:199], v[38:39], v[56:57]
	v_pk_fma_f32 v[8:9], v[194:195], v[6:7], v[8:9]
	v_pk_fma_f32 v[24:25], v[194:195], v[22:23], v[24:25]
	v_pk_fma_f32 v[40:41], v[192:193], v[38:39], v[40:41]
	v_pk_fma_f32 v[56:57], v[192:193], v[54:55], v[56:57]
	v_cvt_pk_bf16_f32 v127, v6, v22
	v_cvt_pk_bf16_f32 v129, v38, v54
	v_cvt_pk_bf16_f32 v133, v7, v23
	v_cvt_pk_bf16_f32 v135, v39, v55
	ds_write2_b32 v242, v127, v129 offset0:204 offset1:236
	ds_write2_b32 v247, v133, v135 offset0:204 offset1:236
	v_pk_fma_f32 v[10:11], v[202:203], v[24:25], v[10:11]
	v_pk_fma_f32 v[26:27], v[200:201], v[8:9], v[26:27]
	v_pk_fma_f32 v[42:43], v[196:197], v[56:57], v[42:43]
	v_pk_fma_f32 v[58:59], v[198:199], v[40:41], v[58:59]
	v_pk_fma_f32 v[10:11], v[194:195], v[8:9], v[10:11]
	v_pk_fma_f32 v[26:27], v[194:195], v[24:25], v[26:27]
	v_pk_fma_f32 v[42:43], v[192:193], v[40:41], v[42:43]
	v_pk_fma_f32 v[58:59], v[192:193], v[56:57], v[58:59]
	v_cvt_pk_bf16_f32 v119, v8, v24
	v_cvt_pk_bf16_f32 v121, v40, v56
	v_cvt_pk_bf16_f32 v123, v9, v25
	v_cvt_pk_bf16_f32 v125, v41, v57
	ds_write2_b32 v245, v119, v121 offset0:0 offset1:32
	ds_write2_b32 v106, v123, v125 offset0:0 offset1:32
	v_pk_fma_f32 v[12:13], v[202:203], v[26:27], v[12:13]
	v_pk_fma_f32 v[28:29], v[200:201], v[10:11], v[28:29]
	v_pk_fma_f32 v[44:45], v[196:197], v[58:59], v[44:45]
	v_pk_fma_f32 v[60:61], v[198:199], v[42:43], v[60:61]
	v_pk_fma_f32 v[12:13], v[194:195], v[10:11], v[12:13]
	v_pk_fma_f32 v[28:29], v[194:195], v[26:27], v[28:29]
	v_pk_fma_f32 v[44:45], v[192:193], v[42:43], v[44:45]
	v_pk_fma_f32 v[60:61], v[192:193], v[58:59], v[60:61]
	v_cvt_pk_bf16_f32 v127, v10, v26
	v_cvt_pk_bf16_f32 v129, v42, v58
	v_cvt_pk_bf16_f32 v133, v11, v27
	v_cvt_pk_bf16_f32 v135, v43, v59
	ds_write2_b32 v245, v127, v129 offset0:68 offset1:100
	ds_write2_b32 v106, v133, v135 offset0:68 offset1:100
	v_pk_fma_f32 v[14:15], v[202:203], v[28:29], v[14:15]
	v_pk_fma_f32 v[30:31], v[200:201], v[12:13], v[30:31]
	v_pk_fma_f32 v[46:47], v[196:197], v[60:61], v[46:47]
	v_pk_fma_f32 v[62:63], v[198:199], v[44:45], v[62:63]
	v_pk_fma_f32 v[216:217], v[194:195], v[12:13], v[14:15]
	v_pk_fma_f32 v[206:207], v[194:195], v[28:29], v[30:31]
	v_pk_fma_f32 v[214:215], v[192:193], v[44:45], v[46:47]
	v_pk_fma_f32 v[204:205], v[192:193], v[60:61], v[62:63]
	v_cvt_pk_bf16_f32 v119, v12, v28
	v_cvt_pk_bf16_f32 v121, v44, v60
	v_cvt_pk_bf16_f32 v123, v13, v29
	v_cvt_pk_bf16_f32 v125, v45, v61
	ds_write2_b32 v245, v119, v121 offset0:136 offset1:168
	ds_write2_b32 v106, v123, v125 offset0:136 offset1:168
	v_cvt_pk_bf16_f32 v127, v216, v206
	v_cvt_pk_bf16_f32 v129, v214, v204
	v_cvt_pk_bf16_f32 v133, v217, v207
	v_cvt_pk_bf16_f32 v135, v215, v205
	ds_write2_b32 v245, v127, v129 offset0:204 offset1:236
	ds_write2_b32 v106, v133, v135 offset0:204 offset1:236
	s_waitcnt lgkmcnt(0)
	ds_read_b128 v[0:3], v244
	ds_read_b128 v[4:7], v244 offset:64
	ds_read_b128 v[8:11], v244 offset:128
	ds_read_b128 v[12:15], v244 offset:192
	ds_read_b128 v[16:19], v244 offset:4352
	ds_read_b128 v[20:23], v244 offset:4416
	ds_read_b128 v[24:27], v244 offset:4480
	ds_read_b128 v[28:31], v244 offset:4544
	s_waitcnt lgkmcnt(7)
	v_mfma_f32_16x16x32_bf16 v[32:35], v[80:83], v[0:3], 0
	s_waitcnt lgkmcnt(3)
	v_mfma_f32_16x16x32_bf16 v[36:39], v[80:83], v[16:19], 0
	s_waitcnt lgkmcnt(2)
	v_mfma_f32_16x16x32_bf16 v[32:35], v[76:79], v[4:7], v[32:35]
	v_mfma_f32_16x16x32_bf16 v[36:39], v[76:79], v[20:23], v[36:39]
	s_waitcnt lgkmcnt(1)
	v_mfma_f32_16x16x32_bf16 v[32:35], v[72:75], v[8:11], v[32:35]
	v_mfma_f32_16x16x32_bf16 v[36:39], v[72:75], v[24:27], v[36:39]
	s_waitcnt lgkmcnt(0)
; #define LAS __attribute__((address_space(3)))
; __device__ __forceinline__ unsigned cvt_pk(float lo, float hi) { unsigned r; asm volatile("v_cvt_pk_bf16_f32 %0, %1, %2" : "=v"(r) : "v"(lo), "v"(hi)); return r; }
; __device__ __forceinline__ float bf_lo(unsigned w) { return __uint_as_float(w << 16); }
; __device__ __forceinline__ float bf_hi(unsigned w) { return __uint_as_float(w & 0xffff0000u); }
; #define LDS_WAIT() asm volatile("s_waitcnt lgkmcnt(0)" ::: "memory")
; __device__ __forceinline__ float gelu_tanh(float y) { const float t = y + 0.044715f * y * y * y; return y * __builtin_amdgcn_rcpf(1.0f + __builtin_amdgcn_exp2f(-2.302208198f * t)); }
; template <bool FINAL>
; __device__ __forceinline__ void ssm_item(const Args& a, LAS unsigned char* lds, int item, int wave, int lane) {
;     ...
;         if (FINAL) {
;             LDS_WAIT(); asm volatile("" ::: "memory");
; #pragma unroll
;             for (int bh = 0; bh < 2; ++bh) {
;                 f32x4 Y = (f32x4){0.f, 0.f, 0.f, 0.f};
; #pragma unroll
;                 for (int k = 0; k < 4; ++k) { const bf16x8 sf = *(const LAS bf16x8*)(sl + (bh * 16 + (lane & 15)) * SP + (32 * k + 8 * (lane >> 4)) * 2);
;                     Y = __builtin_amdgcn_mfma_f32_16x16x32_bf16(cmf[k], sf, Y, 0, 0, 0); }
;                 const u32x2 uu = bh ? uu1 : uu0;
;                 const float y0 = Y[0] + dsk.x * bf_lo(uu.x), y1 = Y[1] + dsk.y * bf_hi(uu.x), y2 = Y[2] + dsk.z * bf_lo(uu.y), y3 = Y[3] + dsk.w * bf_hi(uu.y);
;                 u32x2 w; w.x = cvt_pk(gelu_tanh(y0), gelu_tanh(y1)); w.y = cvt_pk(gelu_tanh(y2), gelu_tanh(y3));
;                 *(u32x2*)(ze + (size_t)st * 8 * DM + (size_t)bh * SEQ * DM) = w;
;             }
	v_mfma_f32_16x16x32_bf16 v[32:35], v[68:71], v[12:15], v[32:35]
	v_mfma_f32_16x16x32_bf16 v[36:39], v[68:71], v[28:31], v[36:39]
	v_lshlrev_b32_e32 v48, 16, v252
	v_and_b32_e32 v49, 0xffff0000, v252
	v_lshlrev_b32_e32 v50, 16, v253
	v_and_b32_e32 v51, 0xffff0000, v253
	v_lshlrev_b32_e32 v52, 16, v254
	v_and_b32_e32 v53, 0xffff0000, v254
	v_lshlrev_b32_e32 v54, 16, v255
	v_and_b32_e32 v55, 0xffff0000, v255
	s_nop 1
	v_pk_fma_f32 v[32:33], v[64:65], v[48:49], v[32:33]
	v_pk_fma_f32 v[34:35], v[66:67], v[50:51], v[34:35]
	v_pk_fma_f32 v[36:37], v[64:65], v[52:53], v[36:37]
	v_pk_fma_f32 v[38:39], v[66:67], v[54:55], v[38:39]
	v_pk_mul_f32 v[40:41], v[32:33], v[32:33]
	v_pk_mul_f32 v[42:43], v[34:35], v[34:35]
	v_pk_mul_f32 v[44:45], v[36:37], v[36:37]
	v_pk_mul_f32 v[46:47], v[38:39], v[38:39]
	v_pk_fma_f32 v[40:41], v[40:41], s[62:63], v[246:247] op_sel_hi:[1,1,0]
	v_pk_fma_f32 v[42:43], v[42:43], s[62:63], v[246:247] op_sel_hi:[1,1,0]
	v_pk_fma_f32 v[44:45], v[44:45], s[62:63], v[246:247] op_sel_hi:[1,1,0]
	v_pk_fma_f32 v[46:47], v[46:47], s[62:63], v[246:247] op_sel_hi:[1,1,0]
	v_pk_mul_f32 v[40:41], v[32:33], v[40:41]
	v_pk_mul_f32 v[42:43], v[34:35], v[42:43]
	v_pk_mul_f32 v[44:45], v[36:37], v[44:45]
	v_pk_mul_f32 v[46:47], v[38:39], v[46:47]
	v_exp_f32_e32 v40, v40
	v_exp_f32_e32 v41, v41
	v_exp_f32_e32 v42, v42
	v_exp_f32_e32 v43, v43
	v_exp_f32_e32 v44, v44
	v_exp_f32_e32 v45, v45
	v_exp_f32_e32 v46, v46
	v_exp_f32_e32 v47, v47
	v_pk_add_f32 v[40:41], v[40:41], s[64:65]
	v_pk_add_f32 v[42:43], v[42:43], s[64:65]
	v_pk_add_f32 v[44:45], v[44:45], s[64:65]
	v_pk_add_f32 v[46:47], v[46:47], s[64:65]
	v_rcp_f32_e32 v40, v40
	v_rcp_f32_e32 v41, v41
	v_rcp_f32_e32 v42, v42
	v_rcp_f32_e32 v43, v43
	v_rcp_f32_e32 v44, v44
	v_rcp_f32_e32 v45, v45
	v_rcp_f32_e32 v46, v46
	v_rcp_f32_e32 v47, v47
	v_pk_mul_f32 v[32:33], v[32:33], v[40:41]
	v_pk_mul_f32 v[34:35], v[34:35], v[42:43]
	v_pk_mul_f32 v[36:37], v[36:37], v[44:45]
	v_pk_mul_f32 v[38:39], v[38:39], v[46:47]
	s_nop 0
	v_cvt_pk_bf16_f32 v40, v32, v33
	v_cvt_pk_bf16_f32 v41, v34, v35
	v_cvt_pk_bf16_f32 v42, v36, v37
	v_cvt_pk_bf16_f32 v43, v38, v39
	s_nop 1
	v_permlane16_swap_b32 v40, v42
	v_permlane16_swap_b32 v41, v43
	global_store_dwordx4 v137, v[40:43], s[70:71]
	v_add_u32_e32 v137, 0x4000, v137
	s_waitcnt vmcnt(3)
	ds_write_b128 v141, v[248:251]
	ds_read_b64 v[252:253], v143
	ds_read_b64 v[254:255], v143 offset:128
	v_mfma_f32_32x32x16_bf16 v[0:15], v[248:251], v[88:91], 0
	v_mfma_f32_32x32x16_bf16 v[16:31], v[248:251], v[92:95], 0
	v_mfma_f32_32x32x16_bf16 v[32:47], v[248:251], v[96:99], 0
	v_mfma_f32_32x32x16_bf16 v[48:63], v[248:251], v[84:87], 0
	s_nop 15
	global_load_dwordx4 v[248:251], v139, s[58:59]
	v_add_u32_e32 v139, 0x4000, v139
	v_pk_fma_f32 v[0:1], v[202:203], v[206:207], v[0:1]
	v_pk_fma_f32 v[16:17], v[200:201], v[216:217], v[16:17]
	v_pk_fma_f32 v[32:33], v[196:197], v[204:205], v[32:33]
	v_pk_fma_f32 v[48:49], v[198:199], v[214:215], v[48:49]
	v_pk_fma_f32 v[0:1], v[194:195], v[216:217], v[0:1]
	v_pk_fma_f32 v[16:17], v[194:195], v[206:207], v[16:17]
	v_pk_fma_f32 v[32:33], v[192:193], v[214:215], v[32:33]
	v_pk_fma_f32 v[48:49], v[192:193], v[204:205], v[48:49]
	v_pk_fma_f32 v[2:3], v[202:203], v[16:17], v[2:3]
	v_pk_fma_f32 v[18:19], v[200:201], v[0:1], v[18:19]
	v_pk_fma_f32 v[34:35], v[196:197], v[48:49], v[34:35]
	v_pk_fma_f32 v[50:51], v[198:199], v[32:33], v[50:51]
	v_pk_fma_f32 v[2:3], v[194:195], v[0:1], v[2:3]
	v_pk_fma_f32 v[18:19], v[194:195], v[16:17], v[18:19]
	v_pk_fma_f32 v[34:35], v[192:193], v[32:33], v[34:35]
	v_pk_fma_f32 v[50:51], v[192:193], v[48:49], v[50:51]
	v_cvt_pk_bf16_f32 v119, v0, v16
	v_cvt_pk_bf16_f32 v121, v32, v48
	v_cvt_pk_bf16_f32 v123, v1, v17
	v_cvt_pk_bf16_f32 v125, v33, v49
	ds_write2_b32 v242, v119, v121 offset0:0 offset1:32
	ds_write2_b32 v247, v123, v125 offset0:0 offset1:32
	v_pk_fma_f32 v[4:5], v[202:203], v[18:19], v[4:5]
	v_pk_fma_f32 v[20:21], v[200:201], v[2:3], v[20:21]
	v_pk_fma_f32 v[36:37], v[196:197], v[50:51], v[36:37]
	v_pk_fma_f32 v[52:53], v[198:199], v[34:35], v[52:53]
	v_pk_fma_f32 v[4:5], v[194:195], v[2:3], v[4:5]
	v_pk_fma_f32 v[20:21], v[194:195], v[18:19], v[20:21]
	v_pk_fma_f32 v[36:37], v[192:193], v[34:35], v[36:37]
	v_pk_fma_f32 v[52:53], v[192:193], v[50:51], v[52:53]
	v_cvt_pk_bf16_f32 v127, v2, v18
	v_cvt_pk_bf16_f32 v129, v34, v50
	v_cvt_pk_bf16_f32 v133, v3, v19
	v_cvt_pk_bf16_f32 v135, v35, v51
	ds_write2_b32 v242, v127, v129 offset0:68 offset1:100
	ds_write2_b32 v247, v133, v135 offset0:68 offset1:100
	v_pk_fma_f32 v[6:7], v[202:203], v[20:21], v[6:7]
	v_pk_fma_f32 v[22:23], v[200:201], v[4:5], v[22:23]
	v_pk_fma_f32 v[38:39], v[196:197], v[52:53], v[38:39]
	v_pk_fma_f32 v[54:55], v[198:199], v[36:37], v[54:55]
	v_pk_fma_f32 v[6:7], v[194:195], v[4:5], v[6:7]
	v_pk_fma_f32 v[22:23], v[194:195], v[20:21], v[22:23]
	v_pk_fma_f32 v[38:39], v[192:193], v[36:37], v[38:39]
	v_pk_fma_f32 v[54:55], v[192:193], v[52:53], v[54:55]
	v_cvt_pk_bf16_f32 v119, v4, v20
	v_cvt_pk_bf16_f32 v121, v36, v52
	v_cvt_pk_bf16_f32 v123, v5, v21
	v_cvt_pk_bf16_f32 v125, v37, v53
	ds_write2_b32 v242, v119, v121 offset0:136 offset1:168
	ds_write2_b32 v247, v123, v125 offset0:136 offset1:168
	v_pk_fma_f32 v[8:9], v[202:203], v[22:23], v[8:9]
	v_pk_fma_f32 v[24:25], v[200:201], v[6:7], v[24:25]
	v_pk_fma_f32 v[40:41], v[196:197], v[54:55], v[40:41]
	v_pk_fma_f32 v[56:57], v[198:199], v[38:39], v[56:57]
	v_pk_fma_f32 v[8:9], v[194:195], v[6:7], v[8:9]
	v_pk_fma_f32 v[24:25], v[194:195], v[22:23], v[24:25]
	v_pk_fma_f32 v[40:41], v[192:193], v[38:39], v[40:41]
	v_pk_fma_f32 v[56:57], v[192:193], v[54:55], v[56:57]
; #define LAS __attribute__((address_space(3)))
; __device__ __forceinline__ unsigned cvt_pk(float lo, float hi) { unsigned r; asm volatile("v_cvt_pk_bf16_f32 %0, %1, %2" : "=v"(r) : "v"(lo), "v"(hi)); return r; }
; template <bool FINAL>
; __device__ __forceinline__ void ssm_item(const Args& a, LAS unsigned char* lds, int item, int wave, int lane) {
;     ...
;         for (int t = 0; t < 8; ++t) {
;             const f32x2 x0r = (f32x2){X[0][2 * t], X[0][2 * t + 1]}, x0i = (f32x2){X[1][2 * t], X[1][2 * t + 1]}, x1r = (f32x2){X[2][2 * t], X[2][2 * t + 1]}, x1i = (f32x2){X[3][2 * t], X[3][2 * t + 1]};
;             const f32x2 n0r = pk_fma(a0x, s0r, pk_fma(na0y, s0i, x0r)), n0i = pk_fma(a0x, s0i, pk_fma(a0y, s0r, x0i));
;             const f32x2 n1r = pk_fma(a1x, s1r, pk_fma(na1y, s1i, x1r)), n1i = pk_fma(a1x, s1i, pk_fma(a1y, s1r, x1i));
;             s0r = n0r; s0i = n0i; s1r = n1r; s1i = n1i;
;             if (FINAL) {
;                 LAS unsigned char* r0 = sl + ((hi * 2 + 0) * 8 + t) * SP; LAS unsigned char* r1 = sl + ((hi * 2 + 1) * 8 + t) * SP;
;                 *(LAS unsigned*)(r0 + j * 4) = cvt_pk(n0r.x, n0i.x); *(LAS unsigned*)(r0 + (32 + j) * 4) = cvt_pk(n1r.x, n1i.x);
;                 *(LAS unsigned*)(r1 + j * 4) = cvt_pk(n0r.y, n0i.y); *(LAS unsigned*)(r1 + (32 + j) * 4) = cvt_pk(n1r.y, n1i.y); }
;         }
;         if (FINAL) {
;             LDS_WAIT(); asm volatile("" ::: "memory");
; #pragma unroll
;             for (int bh = 0; bh < 2; ++bh) {
;                 f32x4 Y = (f32x4){0.f, 0.f, 0.f, 0.f};
; #pragma unroll
;                 for (int k = 0; k < 4; ++k) { const bf16x8 sf = *(const LAS bf16x8*)(sl + (bh * 16 + (lane & 15)) * SP + (32 * k + 8 * (lane >> 4)) * 2);
;                     Y = __builtin_amdgcn_mfma_f32_16x16x32_bf16(cmf[k], sf, Y, 0, 0, 0); }
;                 const u32x2 uu = bh ? uu1 : uu0;
;                 const float y0 = Y[0] + dsk.x * bf_lo(uu.x), y1 = Y[1] + dsk.y * bf_hi(uu.x), y2 = Y[2] + dsk.z * bf_lo(uu.y), y3 = Y[3] + dsk.w * bf_hi(uu.y);
;                 u32x2 w; w.x = cvt_pk(gelu_tanh(y0), gelu_tanh(y1)); w.y = cvt_pk(gelu_tanh(y2), gelu_tanh(y3));
;                 *(u32x2*)(ze + (size_t)st * 8 * DM + (size_t)bh * SEQ * DM) = w;
;             }
;             LDS_WAIT(); asm volatile("" ::: "memory");
;         }
;         uf = ufn; uu0 = un0; uu1 = un1;
;     }
	v_cvt_pk_bf16_f32 v127, v6, v22
	v_cvt_pk_bf16_f32 v129, v38, v54
	v_cvt_pk_bf16_f32 v133, v7, v23
	v_cvt_pk_bf16_f32 v135, v39, v55
	ds_write2_b32 v242, v127, v129 offset0:204 offset1:236
	ds_write2_b32 v247, v133, v135 offset0:204 offset1:236
	v_pk_fma_f32 v[10:11], v[202:203], v[24:25], v[10:11]
	v_pk_fma_f32 v[26:27], v[200:201], v[8:9], v[26:27]
	v_pk_fma_f32 v[42:43], v[196:197], v[56:57], v[42:43]
	v_pk_fma_f32 v[58:59], v[198:199], v[40:41], v[58:59]
	v_pk_fma_f32 v[10:11], v[194:195], v[8:9], v[10:11]
	v_pk_fma_f32 v[26:27], v[194:195], v[24:25], v[26:27]
	v_pk_fma_f32 v[42:43], v[192:193], v[40:41], v[42:43]
	v_pk_fma_f32 v[58:59], v[192:193], v[56:57], v[58:59]
	v_cvt_pk_bf16_f32 v119, v8, v24
	v_cvt_pk_bf16_f32 v121, v40, v56
	v_cvt_pk_bf16_f32 v123, v9, v25
	v_cvt_pk_bf16_f32 v125, v41, v57
	ds_write2_b32 v245, v119, v121 offset0:0 offset1:32
	ds_write2_b32 v106, v123, v125 offset0:0 offset1:32
	v_pk_fma_f32 v[12:13], v[202:203], v[26:27], v[12:13]
	v_pk_fma_f32 v[28:29], v[200:201], v[10:11], v[28:29]
	v_pk_fma_f32 v[44:45], v[196:197], v[58:59], v[44:45]
	v_pk_fma_f32 v[60:61], v[198:199], v[42:43], v[60:61]
	v_pk_fma_f32 v[12:13], v[194:195], v[10:11], v[12:13]
	v_pk_fma_f32 v[28:29], v[194:195], v[26:27], v[28:29]
	v_pk_fma_f32 v[44:45], v[192:193], v[42:43], v[44:45]
	v_pk_fma_f32 v[60:61], v[192:193], v[58:59], v[60:61]
	v_cvt_pk_bf16_f32 v127, v10, v26
	v_cvt_pk_bf16_f32 v129, v42, v58
	v_cvt_pk_bf16_f32 v133, v11, v27
	v_cvt_pk_bf16_f32 v135, v43, v59
	ds_write2_b32 v245, v127, v129 offset0:68 offset1:100
	ds_write2_b32 v106, v133, v135 offset0:68 offset1:100
	v_pk_fma_f32 v[14:15], v[202:203], v[28:29], v[14:15]
	v_pk_fma_f32 v[30:31], v[200:201], v[12:13], v[30:31]
	v_pk_fma_f32 v[46:47], v[196:197], v[60:61], v[46:47]
	v_pk_fma_f32 v[62:63], v[198:199], v[44:45], v[62:63]
	v_pk_fma_f32 v[216:217], v[194:195], v[12:13], v[14:15]
	v_pk_fma_f32 v[206:207], v[194:195], v[28:29], v[30:31]
	v_pk_fma_f32 v[214:215], v[192:193], v[44:45], v[46:47]
	v_pk_fma_f32 v[204:205], v[192:193], v[60:61], v[62:63]
	v_cvt_pk_bf16_f32 v119, v12, v28
	v_cvt_pk_bf16_f32 v121, v44, v60
	v_cvt_pk_bf16_f32 v123, v13, v29
	v_cvt_pk_bf16_f32 v125, v45, v61
	ds_write2_b32 v245, v119, v121 offset0:136 offset1:168
	ds_write2_b32 v106, v123, v125 offset0:136 offset1:168
	v_cvt_pk_bf16_f32 v127, v216, v206
	v_cvt_pk_bf16_f32 v129, v214, v204
	v_cvt_pk_bf16_f32 v133, v217, v207
	v_cvt_pk_bf16_f32 v135, v215, v205
	ds_write2_b32 v245, v127, v129 offset0:204 offset1:236
	ds_write2_b32 v106, v133, v135 offset0:204 offset1:236
	s_waitcnt lgkmcnt(0)
	ds_read_b128 v[0:3], v244
	ds_read_b128 v[4:7], v244 offset:64
	ds_read_b128 v[8:11], v244 offset:128
	ds_read_b128 v[12:15], v244 offset:192
	ds_read_b128 v[16:19], v244 offset:4352
	ds_read_b128 v[20:23], v244 offset:4416
	ds_read_b128 v[24:27], v244 offset:4480
	ds_read_b128 v[28:31], v244 offset:4544
	s_waitcnt lgkmcnt(7)
	v_mfma_f32_16x16x32_bf16 v[32:35], v[80:83], v[0:3], 0
	s_waitcnt lgkmcnt(3)
	v_mfma_f32_16x16x32_bf16 v[36:39], v[80:83], v[16:19], 0
	s_waitcnt lgkmcnt(2)
	v_mfma_f32_16x16x32_bf16 v[32:35], v[76:79], v[4:7], v[32:35]
	v_mfma_f32_16x16x32_bf16 v[36:39], v[76:79], v[20:23], v[36:39]
	s_waitcnt lgkmcnt(1)
	v_mfma_f32_16x16x32_bf16 v[32:35], v[72:75], v[8:11], v[32:35]
	v_mfma_f32_16x16x32_bf16 v[36:39], v[72:75], v[24:27], v[36:39]
	s_waitcnt lgkmcnt(0)
	v_mfma_f32_16x16x32_bf16 v[32:35], v[68:71], v[12:15], v[32:35]
	v_mfma_f32_16x16x32_bf16 v[36:39], v[68:71], v[28:31], v[36:39]
	v_lshlrev_b32_e32 v48, 16, v252
	v_and_b32_e32 v49, 0xffff0000, v252
	v_lshlrev_b32_e32 v50, 16, v253
	v_and_b32_e32 v51, 0xffff0000, v253
	v_lshlrev_b32_e32 v52, 16, v254
	v_and_b32_e32 v53, 0xffff0000, v254
	v_lshlrev_b32_e32 v54, 16, v255
	v_and_b32_e32 v55, 0xffff0000, v255
	s_nop 1
	v_pk_fma_f32 v[32:33], v[64:65], v[48:49], v[32:33]
	v_pk_fma_f32 v[34:35], v[66:67], v[50:51], v[34:35]
	v_pk_fma_f32 v[36:37], v[64:65], v[52:53], v[36:37]
	v_pk_fma_f32 v[38:39], v[66:67], v[54:55], v[38:39]
	v_pk_mul_f32 v[40:41], v[32:33], v[32:33]
	v_pk_mul_f32 v[42:43], v[34:35], v[34:35]
	v_pk_mul_f32 v[44:45], v[36:37], v[36:37]
	v_pk_mul_f32 v[46:47], v[38:39], v[38:39]
	v_pk_fma_f32 v[40:41], v[40:41], s[62:63], v[246:247] op_sel_hi:[1,1,0]
	v_pk_fma_f32 v[42:43], v[42:43], s[62:63], v[246:247] op_sel_hi:[1,1,0]
	v_pk_fma_f32 v[44:45], v[44:45], s[62:63], v[246:247] op_sel_hi:[1,1,0]
	v_pk_fma_f32 v[46:47], v[46:47], s[62:63], v[246:247] op_sel_hi:[1,1,0]
	v_pk_mul_f32 v[40:41], v[32:33], v[40:41]
	v_pk_mul_f32 v[42:43], v[34:35], v[42:43]
	v_pk_mul_f32 v[44:45], v[36:37], v[44:45]
	v_pk_mul_f32 v[46:47], v[38:39], v[46:47]
	v_exp_f32_e32 v40, v40
	v_exp_f32_e32 v41, v41
	v_exp_f32_e32 v42, v42
	v_exp_f32_e32 v43, v43
	v_exp_f32_e32 v44, v44
	v_exp_f32_e32 v45, v45
	v_exp_f32_e32 v46, v46
	v_exp_f32_e32 v47, v47
	v_pk_add_f32 v[40:41], v[40:41], s[64:65]
	v_pk_add_f32 v[42:43], v[42:43], s[64:65]
	v_pk_add_f32 v[44:45], v[44:45], s[64:65]
	v_pk_add_f32 v[46:47], v[46:47], s[64:65]
	v_rcp_f32_e32 v40, v40
	v_rcp_f32_e32 v41, v41
	v_rcp_f32_e32 v42, v42
	v_rcp_f32_e32 v43, v43
	v_rcp_f32_e32 v44, v44
	v_rcp_f32_e32 v45, v45
	v_rcp_f32_e32 v46, v46
	v_rcp_f32_e32 v47, v47
	v_pk_mul_f32 v[32:33], v[32:33], v[40:41]
	v_pk_mul_f32 v[34:35], v[34:35], v[42:43]
	v_pk_mul_f32 v[36:37], v[36:37], v[44:45]
	v_pk_mul_f32 v[38:39], v[38:39], v[46:47]
	s_add_i32 s12, s12, 1
	s_cmp_lg_u32 s12, 16
	v_cvt_pk_bf16_f32 v40, v32, v33
	v_cvt_pk_bf16_f32 v41, v34, v35
	v_cvt_pk_bf16_f32 v42, v36, v37
	v_cvt_pk_bf16_f32 v43, v38, v39
	s_nop 1
	v_permlane16_swap_b32 v40, v42
	v_permlane16_swap_b32 v41, v43
	global_store_dwordx4 v137, v[40:43], s[70:71]
	v_add_u32_e32 v137, 0x4000, v137
	s_cbranch_scc1 .Lp3_step
	s_add_i32 s20, s20, s92
	s_add_i32 s40, s40, s96
	s_cmpk_gt_i32 s20, 0xff
	s_cbranch_scc0 .LBB0_328
